# filtergen: w3 fragments resident (fetched at item start), MFMA output fused with decay window and bf16 store (staged path kept for the item with position 0)
# speedup vs baseline: 1.0295x; 1.0031x over previous
; __device__ __forceinline__ int obid() { int b = blockIdx.x; asm volatile("" : "+s"(b)); return b; }
; __device__ __forceinline__ int ogrid() { int g = gridDim.x; asm volatile("" : "+s"(g)); return g; }
; __device__ __forceinline__ void ph_filtergen(KP p, int l, unsigned char* sm, int wv) {
;     ...
;     for (int item = obid(); item < 384; item += ogrid()) {
;         const int L = item < 256 ? LP : LSQ, n0 = (item < 256 ? item : item - 256) * 64;
;         bf16_t* kf = p->X + (item < 256 ? 0 : 16777216);
;         __syncthreads();
;         {
;             const int n = n0 + lane;
;             const float w = 2.0f * (float)n / (float)L;
; #pragma unroll
;             for (int q = 0; q < 2; ++q) {
;                 const int b = wid * 2 + q;
;                 const float f = 1e-4f + (float)b * 0.9999933333333334f;
;     ...
;             const int ol = tid & 255, o = pass * 256 + ol, ph0 = (tid >> 8) * 32;
;             float wcol[64];
; #pragma unroll
;             for (int j = 0; j < 64; ++j) wcol[j] = w3[j * 1024 + o];
.LBB0_884:
	v_lshrrev_b32_e32 v128, 6, v18
	v_lshrrev_b32_e32 v131, 5, v19
	v_and_b32_e32 v132, 31, v19
	v_lshl_add_u32 v133, v128, 5, v132
	s_and_b32 s99, s32, 1
	s_lshl_b32 s99, s99, 9
	v_add_u32_e32 v133, s99, v133
	v_lshl_add_u32 v133, v131, 15, v133
	v_lshlrev_b32_e32 v133, 2, v133
	s_mov_b64 s[98:99], s[2:3]
	global_load_dword v176, v133, s[98:99]
	global_load_dword v210, v133, s[98:99] offset:1024
	s_add_u32 s98, s98, 0x1000
	s_addc_u32 s99, s99, 0
	global_load_dword v177, v133, s[98:99]
	global_load_dword v211, v133, s[98:99] offset:1024
	s_add_u32 s98, s98, 0x1000
	s_addc_u32 s99, s99, 0
	global_load_dword v178, v133, s[98:99]
	global_load_dword v212, v133, s[98:99] offset:1024
	s_add_u32 s98, s98, 0x1000
	s_addc_u32 s99, s99, 0
	global_load_dword v179, v133, s[98:99]
	global_load_dword v213, v133, s[98:99] offset:1024
	s_add_u32 s98, s98, 0x1000
	s_addc_u32 s99, s99, 0
	global_load_dword v180, v133, s[98:99]
	global_load_dword v214, v133, s[98:99] offset:1024
	s_add_u32 s98, s98, 0x1000
	s_addc_u32 s99, s99, 0
	global_load_dword v181, v133, s[98:99]
	global_load_dword v215, v133, s[98:99] offset:1024
	s_add_u32 s98, s98, 0x1000
	s_addc_u32 s99, s99, 0
	global_load_dword v182, v133, s[98:99]
	global_load_dword v216, v133, s[98:99] offset:1024
	s_add_u32 s98, s98, 0x1000
	s_addc_u32 s99, s99, 0
	global_load_dword v183, v133, s[98:99]
	global_load_dword v217, v133, s[98:99] offset:1024
	s_add_u32 s98, s98, 0x1000
	s_addc_u32 s99, s99, 0
	global_load_dword v184, v133, s[98:99]
	global_load_dword v218, v133, s[98:99] offset:1024
	s_add_u32 s98, s98, 0x1000
	s_addc_u32 s99, s99, 0
	global_load_dword v185, v133, s[98:99]
	global_load_dword v219, v133, s[98:99] offset:1024
	s_add_u32 s98, s98, 0x1000
	s_addc_u32 s99, s99, 0
	global_load_dword v186, v133, s[98:99]
	global_load_dword v220, v133, s[98:99] offset:1024
	s_add_u32 s98, s98, 0x1000
	s_addc_u32 s99, s99, 0
	global_load_dword v187, v133, s[98:99]
	global_load_dword v221, v133, s[98:99] offset:1024
	s_add_u32 s98, s98, 0x1000
	s_addc_u32 s99, s99, 0
	global_load_dword v188, v133, s[98:99]
	global_load_dword v222, v133, s[98:99] offset:1024
	s_add_u32 s98, s98, 0x1000
	s_addc_u32 s99, s99, 0
	global_load_dword v189, v133, s[98:99]
	global_load_dword v223, v133, s[98:99] offset:1024
	s_add_u32 s98, s98, 0x1000
	s_addc_u32 s99, s99, 0
	global_load_dword v190, v133, s[98:99]
	global_load_dword v224, v133, s[98:99] offset:1024
	s_add_u32 s98, s98, 0x1000
	s_addc_u32 s99, s99, 0
	global_load_dword v191, v133, s[98:99]
	global_load_dword v225, v133, s[98:99] offset:1024
	s_add_u32 s98, s98, 0x1000
	s_addc_u32 s99, s99, 0
	global_load_dword v192, v133, s[98:99]
	global_load_dword v226, v133, s[98:99] offset:1024
	s_add_u32 s98, s98, 0x1000
	s_addc_u32 s99, s99, 0
	global_load_dword v193, v133, s[98:99]
	global_load_dword v227, v133, s[98:99] offset:1024
	s_add_u32 s98, s98, 0x1000
	s_addc_u32 s99, s99, 0
	global_load_dword v194, v133, s[98:99]
	global_load_dword v228, v133, s[98:99] offset:1024
	s_add_u32 s98, s98, 0x1000
	s_addc_u32 s99, s99, 0
	global_load_dword v195, v133, s[98:99]
	global_load_dword v229, v133, s[98:99] offset:1024
	s_add_u32 s98, s98, 0x1000
	s_addc_u32 s99, s99, 0
	global_load_dword v196, v133, s[98:99]
	global_load_dword v232, v133, s[98:99] offset:1024
	s_add_u32 s98, s98, 0x1000
	s_addc_u32 s99, s99, 0
	global_load_dword v197, v133, s[98:99]
	global_load_dword v233, v133, s[98:99] offset:1024
	s_add_u32 s98, s98, 0x1000
	s_addc_u32 s99, s99, 0
	global_load_dword v198, v133, s[98:99]
	global_load_dword v234, v133, s[98:99] offset:1024
	s_add_u32 s98, s98, 0x1000
	s_addc_u32 s99, s99, 0
	global_load_dword v199, v133, s[98:99]
	global_load_dword v235, v133, s[98:99] offset:1024
	s_add_u32 s98, s98, 0x1000
	s_addc_u32 s99, s99, 0
	global_load_dword v200, v133, s[98:99]
	global_load_dword v245, v133, s[98:99] offset:1024
	s_add_u32 s98, s98, 0x1000
	s_addc_u32 s99, s99, 0
	global_load_dword v201, v133, s[98:99]
	global_load_dword v246, v133, s[98:99] offset:1024
	s_add_u32 s98, s98, 0x1000
	s_addc_u32 s99, s99, 0
	global_load_dword v202, v133, s[98:99]
	global_load_dword v247, v133, s[98:99] offset:1024
	s_add_u32 s98, s98, 0x1000
	s_addc_u32 s99, s99, 0
	global_load_dword v203, v133, s[98:99]
	global_load_dword v248, v133, s[98:99] offset:1024
	s_add_u32 s98, s98, 0x1000
	s_addc_u32 s99, s99, 0
	global_load_dword v206, v133, s[98:99]
	global_load_dword v249, v133, s[98:99] offset:1024
	s_add_u32 s98, s98, 0x1000
	s_addc_u32 s99, s99, 0
	global_load_dword v207, v133, s[98:99]
	global_load_dword v250, v133, s[98:99] offset:1024
	s_add_u32 s98, s98, 0x1000
	s_addc_u32 s99, s99, 0
	global_load_dword v208, v133, s[98:99]
	global_load_dword v251, v133, s[98:99] offset:1024
	s_add_u32 s98, s98, 0x1000
	s_addc_u32 s99, s99, 0
	global_load_dword v209, v133, s[98:99]
	global_load_dword v143, v133, s[98:99] offset:1024
	s_lshr_b32 s28, s32, 1
	s_lshl_b32 s14, s28, 6
	s_add_i32 s15, s14, 0xffffc000
	s_cmpk_lt_i32 s28, 0x100
	s_cselect_b64 s[8:9], -1, 0
	s_and_b64 s[0:1], s[8:9], exec
	s_cselect_b32 s0, s14, s15
	v_or_b32_e32 v32, s0, v19
	v_cvt_f32_i32_e32 v0, v32
	s_cselect_b32 s14, s97, 0x2000
	v_cvt_f32_u32_e32 v2, s14
	v_mov_b32_e32 v12, 0xbf1f24be
	v_add_f32_e32 v3, v0, v0
	s_waitcnt lgkmcnt(0)
	v_div_scale_f32 v4, s[0:1], v2, v2, v3
	v_rcp_f32_e32 v5, v4
	s_barrier
; __device__ __forceinline__ float2 twid_precise(float turns) { float s_, c_; sincospif(2.0f * turns, &s_, &c_); return make_float2(c_, s_); }
; __device__ __forceinline__ void ph_filtergen(KP p, int l, unsigned char* sm, int wv) {
;     ...
;         {
;             const int n = n0 + lane;
;             const float w = 2.0f * (float)n / (float)L;
; #pragma unroll
;             for (int q = 0; q < 2; ++q) {
;                 const int b = wid * 2 + q;
;                 const float f = 1e-4f + (float)b * 0.9999933333333334f;
;                 const float ht = f * w, red = ht - 2.0f * rintf(0.5f * ht);
;                 const float2 cs = twid_precise(0.5f * red);
;                 zf[lane * 34 + 1 + b] = cs.x; zf[lane * 34 + 17 + b] = -cs.y;
;             }
;             if (wid == 0) zf[lane * 34] = (float)n / (float)(L - 1);
	v_fma_f32 v6, -v4, v5, 1.0
	v_fmac_f32_e32 v5, v6, v5
	v_div_scale_f32 v6, vcc, v3, v2, v3
	v_mul_f32_e32 v7, v6, v5
	v_fma_f32 v8, -v4, v7, v6
	v_fmac_f32_e32 v7, v8, v5
	v_fma_f32 v4, -v4, v7, v6
	v_div_fmas_f32 v4, v4, v5, v7
	v_div_fixup_f32 v2, v4, v2, v3
	v_pk_mul_f32 v[2:3], v[20:21], v[2:3] op_sel_hi:[1,0]
	s_nop 0
	v_mul_f32_e32 v4, 0.5, v2
	v_mul_f32_e32 v5, 0.5, v3
	v_rndne_f32_e32 v4, v4
	v_rndne_f32_e32 v5, v5
	v_pk_fma_f32 v[2:3], v[4:5], -2.0, v[2:3] op_sel_hi:[1,0,1]
	s_nop 0
	v_pk_mul_f32 v[2:3], v[2:3], 0.5 op_sel_hi:[1,0]
	s_nop 0
	v_pk_add_f32 v[2:3], v[2:3], v[2:3]
	s_nop 0
	v_and_b32_e32 v5, 0x7fffffff, v3
	v_and_b32_e32 v4, 0x7fffffff, v2
	v_pk_mul_f32 v[6:7], v[4:5], 0.5 op_sel_hi:[1,0]
	v_cmp_gt_f32_e64 s[0:1], |v3|, 1.0
	v_floor_f32_e32 v9, v7
	v_floor_f32_e32 v8, v6
	v_sub_f32_e32 v9, v7, v9
	v_sub_f32_e32 v8, v6, v8
	v_min_f32_e32 v9, 0x3f7fffff, v9
	v_cmp_u_f32_e32 vcc, v7, v7
	v_min_f32_e32 v8, 0x3f7fffff, v8
	v_xor_b32_e32 v5, v5, v3
	v_cndmask_b32_e32 v9, v9, v7, vcc
	v_cmp_u_f32_e32 vcc, v6, v6
	v_xor_b32_e32 v4, v4, v2
	s_nop 0
	v_cndmask_b32_e32 v8, v8, v6, vcc
	v_pk_add_f32 v[8:9], v[8:9], v[8:9]
	v_cmp_class_f32_e32 vcc, v6, v239
	s_nop 1
	v_cndmask_b32_e64 v6, v8, 0, vcc
	v_cmp_class_f32_e32 vcc, v7, v239
	s_nop 1
	v_cndmask_b32_e64 v7, v9, 0, vcc
	v_cndmask_b32_e64 v7, |v3|, v7, s[0:1]
	v_cmp_gt_f32_e64 s[0:1], |v2|, 1.0
	v_add_f32_e32 v9, v7, v7
	v_rndne_f32_e32 v9, v9
	v_cndmask_b32_e64 v6, |v2|, v6, s[0:1]
	v_add_f32_e32 v8, v6, v6
	v_rndne_f32_e32 v8, v8
	v_pk_fma_f32 v[6:7], v[8:9], -0.5, v[6:7] op_sel_hi:[1,0,1]
	s_mov_b32 s0, 0x3e75aa41
	v_pk_mul_f32 v[10:11], v[6:7], v[6:7]
	s_nop 0
	v_pk_fma_f32 v[12:13], v[10:11], s[0:1], v[12:13] op_sel_hi:[1,0,0]
	s_mov_b32 s0, 0x40234736
	v_pk_fma_f32 v[12:13], v[10:11], v[12:13], s[0:1] op_sel_hi:[1,1,0]
	s_mov_b32 s0, 0xc0a55e0e
	v_pk_fma_f32 v[12:13], v[10:11], v[12:13], s[0:1] op_sel_hi:[1,1,0]
	v_pk_mul_f32 v[14:15], v[6:7], v[10:11]
	s_mov_b32 s0, 0x40490fdb
	v_pk_mul_f32 v[12:13], v[14:15], v[12:13]
	s_nop 0
	v_pk_fma_f32 v[6:7], v[6:7], s[0:1], v[12:13] op_sel_hi:[1,0,1]
	v_cvt_i32_f32_e32 v13, v8
	s_mov_b32 s0, 0x3d4be544
	v_mov_b32_e32 v8, 0x3e642e9d
	v_cvt_i32_f32_e32 v12, v9
	v_pk_fma_f32 v[8:9], v[10:11], s[0:1], v[8:9] op_sel_hi:[1,0,0]
	s_mov_b32 s0, 0xbfaad1da
	v_pk_fma_f32 v[8:9], v[10:11], v[8:9], s[0:1] op_sel_hi:[1,1,0]
	s_mov_b32 s0, 0x4081e0d3
	v_pk_fma_f32 v[8:9], v[10:11], v[8:9], s[0:1] op_sel_hi:[1,1,0]
	s_mov_b32 s0, 0xc09de9e6
	v_pk_fma_f32 v[8:9], v[10:11], v[8:9], s[0:1] op_sel_hi:[1,1,0]
	s_nop 0
	v_pk_fma_f32 v[8:9], v[10:11], v[8:9], 1.0 op_sel_hi:[1,1,0]
	v_and_b32_e32 v10, 1, v12
	v_and_b32_e32 v11, 1, v13
	v_lshlrev_b32_e32 v12, 30, v12
	v_lshlrev_b32_e32 v13, 30, v13
	v_cmp_eq_u32_e32 vcc, 0, v10
	v_cmp_eq_u32_e64 s[0:1], 0, v11
	v_and_b32_e32 v12, 0x80000000, v12
	v_and_b32_e32 v13, 0x80000000, v13
	v_cndmask_b32_e32 v10, v9, v7, vcc
	v_cndmask_b32_e64 v11, v8, v6, s[0:1]
	v_cndmask_b32_e64 v7, -v7, v9, vcc
	v_cndmask_b32_e64 v6, -v6, v8, s[0:1]
	v_xor_b32_e32 v7, v12, v7
	v_xor_b32_e32 v6, v13, v6
	v_cmp_class_f32_e32 vcc, v3, v242
	v_cmp_class_f32_e64 s[0:1], v2, v242
	v_xor_b32_e32 v5, v5, v10
	v_xor_b32_e32 v4, v4, v11
	v_cndmask_b32_e32 v3, v204, v7, vcc
	v_cndmask_b32_e64 v2, v204, v6, s[0:1]
	v_xor_b32_e32 v5, v5, v12
	v_xor_b32_e32 v4, v4, v13
	ds_write2_b32 v88, v2, v3 offset0:1 offset1:2
	v_mov_b32_e32 v3, 0xffc00000
	v_cndmask_b32_e64 v2, v3, -v5, vcc
	v_cndmask_b32_e64 v3, v3, -v4, s[0:1]
	ds_write2_b32 v88, v3, v2 offset0:17 offset1:18
	s_and_saveexec_b64 s[0:1], s[4:5]
	s_cbranch_execz .LBB0_886
	s_add_i32 s15, s14, -1
	v_cvt_f32_u32_e32 v2, s15
	v_div_scale_f32 v3, s[16:17], v2, v2, v0
	v_rcp_f32_e32 v4, v3
	v_div_scale_f32 v5, vcc, v0, v2, v0
	v_fma_f32 v6, -v3, v4, 1.0
	v_fmac_f32_e32 v4, v6, v4
	v_mul_f32_e32 v6, v5, v4
	v_fma_f32 v7, -v3, v6, v5
	v_fmac_f32_e32 v6, v7, v4
	v_fma_f32 v3, -v3, v6, v5
	v_div_fmas_f32 v3, v3, v4, v6
	v_div_fixup_f32 v2, v3, v2, v0
	ds_write_b32 v31, v2

; __device__ __forceinline__ unsigned pk2(float lo, float hi) { unsigned r; asm volatile("v_cvt_pk_bf16_f32 %0, %1, %2" : "=v"(r) : "v"(lo), "v"(hi)); return r; }
; __device__ __forceinline__ void ph_filtergen(KP p, int l, unsigned char* sm, int wv) {
;     ...
;         for (int pass = 0; pass < 4; ++pass) {
;             const int ol = tid & 255, o = pass * 256 + ol, ph0 = (tid >> 8) * 32;
;             float wcol[64];
; #pragma unroll
;             for (int j = 0; j < 64; ++j) wcol[j] = w3[j * 1024 + o];
; #pragma unroll 2
;             for (int pp = 0; pp < 32; ++pp) {
;                 const f32x4* hr = (const f32x4*)(h2 + (ph0 + pp) * 68);
;                 float acc0 = 0.f, acc1 = 0.f;
; #pragma unroll
;                 for (int j4 = 0; j4 < 16; ++j4) { const f32x4 hv = hr[j4]; acc0 += hv.x * wcol[j4 * 4] + hv.z * wcol[j4 * 4 + 2]; acc1 += hv.y * wcol[j4 * 4 + 1] + hv.w * wcol[j4 * 4 + 3]; }
;                 ot[ol * 65 + ph0 + pp] = acc0 + acc1;
;             }
;             __syncthreads();
;             for (int e = tid; e < 256 * 64; e += 512) {
;                 const int ol2 = e >> 6, pos = e & 63, o2 = pass * 256 + ol2, c = o2 & 511, n = n0 + pos;
;                 const float tt = (float)n / (float)(L - 1);
;                 const float delta = fabsf(-3.070113457325394f + (float)c * ((-15.350567286626971f + 3.070113457325394f) / 511.0f));
;                 float val = ot[ol2 * 65 + pos] * __expf(-tt * delta);
;                 bf16_t* kc = kf + (size_t)c * (2 * L);
;                 if (o2 < 512) { if (n == 0) val += hb[c]; kc[n] = (bf16_t)(pk2(val, 0.f) & 0xffffu); }
;                 else { if (n >= 1) kc[2 * L - n] = (bf16_t)(pk2(val, 0.f) & 0xffffu); else kc[L] = (bf16_t)0; }
.Lmy_fg_latch:
	s_add_i32 s31, s31, 1
	s_bitcmp0_b32 s31, 0
	s_barrier
	s_cbranch_scc1 .LBB0_883
.LBB0_892:
	s_lshl_b32 s43, s31, 8
	v_lshrrev_b32_e32 v128, 6, v18
	v_lshrrev_b32_e32 v131, 5, v19
	v_and_b32_e32 v132, 31, v19
	v_mul_u32_u24_e32 v129, 0x110, v132
	v_lshl_add_u32 v129, v131, 7, v129
	v_add_u32_e32 v129, 0x6300, v129
	v_lshlrev_b32_e32 v130, 5, v128
	v_lshl_add_u32 v130, v131, 2, v130
	v_mul_u32_u24_e32 v130, 0x104, v130
	v_lshl_add_u32 v130, v132, 2, v130
	v_add_u32_e32 v130, 0x10800, v130
	s_cmp_eq_u32 s28, 0
	s_cbranch_scc1 .Lmy_fg_slow
	s_cmpk_eq_u32 s28, 0x100
	s_cbranch_scc1 .Lmy_fg_slow
	s_bitcmp1_b32 s31, 0
	s_cbranch_scc1 .Lmy_fg_fast_odd
	ds_read_b128 v[96:99], v129 offset:0
	ds_read_b128 v[100:103], v129 offset:16
	ds_read_b128 v[104:107], v129 offset:32
	ds_read_b128 v[108:111], v129 offset:48
	ds_read_b128 v[112:115], v129 offset:64
	ds_read_b128 v[116:119], v129 offset:80
	ds_read_b128 v[120:123], v129 offset:96
	ds_read_b128 v[124:127], v129 offset:112
	s_waitcnt vmcnt(0) lgkmcnt(0)
	v_mfma_f32_32x32x2_f32 v[34:49], v176, v96, 0
	v_mfma_f32_32x32x2_f32 v[34:49], v177, v97, v[34:49]
	v_mfma_f32_32x32x2_f32 v[34:49], v178, v98, v[34:49]
	v_mfma_f32_32x32x2_f32 v[34:49], v179, v99, v[34:49]
	v_mfma_f32_32x32x2_f32 v[34:49], v180, v100, v[34:49]
	v_mfma_f32_32x32x2_f32 v[34:49], v181, v101, v[34:49]
	v_mfma_f32_32x32x2_f32 v[34:49], v182, v102, v[34:49]
	v_mfma_f32_32x32x2_f32 v[34:49], v183, v103, v[34:49]
	v_mfma_f32_32x32x2_f32 v[34:49], v184, v104, v[34:49]
	v_mfma_f32_32x32x2_f32 v[34:49], v185, v105, v[34:49]
	v_mfma_f32_32x32x2_f32 v[34:49], v186, v106, v[34:49]
	v_mfma_f32_32x32x2_f32 v[34:49], v187, v107, v[34:49]
	v_mfma_f32_32x32x2_f32 v[34:49], v188, v108, v[34:49]
	v_mfma_f32_32x32x2_f32 v[34:49], v189, v109, v[34:49]
	v_mfma_f32_32x32x2_f32 v[34:49], v190, v110, v[34:49]
	v_mfma_f32_32x32x2_f32 v[34:49], v191, v111, v[34:49]
	v_mfma_f32_32x32x2_f32 v[34:49], v192, v112, v[34:49]
	v_mfma_f32_32x32x2_f32 v[34:49], v193, v113, v[34:49]
	v_mfma_f32_32x32x2_f32 v[34:49], v194, v114, v[34:49]
	v_mfma_f32_32x32x2_f32 v[34:49], v195, v115, v[34:49]
	v_mfma_f32_32x32x2_f32 v[34:49], v196, v116, v[34:49]
	v_mfma_f32_32x32x2_f32 v[34:49], v197, v117, v[34:49]
	v_mfma_f32_32x32x2_f32 v[34:49], v198, v118, v[34:49]
	v_mfma_f32_32x32x2_f32 v[34:49], v199, v119, v[34:49]
	v_mfma_f32_32x32x2_f32 v[34:49], v200, v120, v[34:49]
	v_mfma_f32_32x32x2_f32 v[34:49], v201, v121, v[34:49]
	v_mfma_f32_32x32x2_f32 v[34:49], v202, v122, v[34:49]
	v_mfma_f32_32x32x2_f32 v[34:49], v203, v123, v[34:49]
	v_mfma_f32_32x32x2_f32 v[34:49], v206, v124, v[34:49]
	v_mfma_f32_32x32x2_f32 v[34:49], v207, v125, v[34:49]
	v_mfma_f32_32x32x2_f32 v[34:49], v208, v126, v[34:49]
	v_mfma_f32_32x32x2_f32 v[34:49], v209, v127, v[34:49]
	v_lshlrev_b32_e32 v63, 2, v132
	ds_bpermute_b32 v52, v63, v94
	v_sub_u32_e32 v50, 0, v131
	v_lshl_add_u32 v50, v50, 5, v32
	s_lshl_b32 s98, 1, s42
	v_mov_b32_e32 v51, v50
	s_cmpk_lt_u32 s43, 0x200
	s_cbranch_scc1 .Lmy_fg_fwd_e_0
	v_sub_u32_e32 v51, s98, v50
.Lmy_fg_fwd_e_0:
	s_and_b32 s99, s43, 0x1ff
	v_lshl_add_u32 v64, v128, 5, s99
	v_lshl_add_u32 v64, v131, 2, v64
	v_cvt_f32_u32_e32 v54, v64
	s_add_i32 s99, s42, 1
	v_lshlrev_b32_e32 v53, s99, v64
	v_lshl_add_u32 v55, v51, 1, v53
	s_lshl_b32 s98, 2, s42
	s_mul_i32 s99, s98, 5
	s_nop 15
	s_nop 3
	s_waitcnt lgkmcnt(0)
	v_add_f32_e32 v57, 0x00000000, v54
	v_add_f32_e32 v58, 0x3f800000, v54
	v_add_f32_e32 v59, 0x40000000, v54
	v_add_f32_e32 v60, 0x40400000, v54
	v_fmamk_f32 v57, v57, 0xbcc4df2d, v238
	v_fmamk_f32 v58, v58, 0xbcc4df2d, v238
	v_fmamk_f32 v59, v59, 0xbcc4df2d, v238
	v_fmamk_f32 v60, v60, 0xbcc4df2d, v238
	v_mul_f32_e64 v57, v52, |v57|
	v_mul_f32_e64 v58, v52, |v58|
	v_mul_f32_e64 v59, v52, |v59|
	v_mul_f32_e64 v60, v52, |v60|
	v_mul_f32_e32 v57, 0x3fb8aa3b, v57
	v_mul_f32_e32 v58, 0x3fb8aa3b, v58
	v_mul_f32_e32 v59, 0x3fb8aa3b, v59
	v_mul_f32_e32 v60, 0x3fb8aa3b, v60
	v_exp_f32_e32 v57, v57
	v_exp_f32_e32 v58, v58
	v_exp_f32_e32 v59, v59
	v_exp_f32_e32 v60, v60
	s_nop 0
	v_mul_f32_e32 v34, v34, v57
	v_mul_f32_e32 v35, v35, v58
	v_mul_f32_e32 v36, v36, v59
	v_mul_f32_e32 v37, v37, v60
	v_cvt_pk_bf16_f32 v61, v34, v35
	v_cvt_pk_bf16_f32 v62, v36, v37
	v_add_u32_e32 v56, s98, v55
	global_store_short v55, v61, s[16:17]
	global_store_short_d16_hi v56, v61, s[16:17]
	v_add_u32_e32 v55, s98, v56
	v_add_u32_e32 v56, s98, v55
	global_store_short v55, v62, s[16:17]
	global_store_short_d16_hi v56, v62, s[16:17]
	v_add_u32_e32 v55, s99, v56
	v_add_f32_e32 v57, 0x41000000, v54
	v_add_f32_e32 v58, 0x41100000, v54
	v_add_f32_e32 v59, 0x41200000, v54
	v_add_f32_e32 v60, 0x41300000, v54
	v_fmamk_f32 v57, v57, 0xbcc4df2d, v238
	v_fmamk_f32 v58, v58, 0xbcc4df2d, v238
	v_fmamk_f32 v59, v59, 0xbcc4df2d, v238
	v_fmamk_f32 v60, v60, 0xbcc4df2d, v238
	v_mul_f32_e64 v57, v52, |v57|
	v_mul_f32_e64 v58, v52, |v58|
	v_mul_f32_e64 v59, v52, |v59|
	v_mul_f32_e64 v60, v52, |v60|
	v_mul_f32_e32 v57, 0x3fb8aa3b, v57
	v_mul_f32_e32 v58, 0x3fb8aa3b, v58
	v_mul_f32_e32 v59, 0x3fb8aa3b, v59
	v_mul_f32_e32 v60, 0x3fb8aa3b, v60
	v_exp_f32_e32 v57, v57
	v_exp_f32_e32 v58, v58
	v_exp_f32_e32 v59, v59
	v_exp_f32_e32 v60, v60
	s_nop 0
	v_mul_f32_e32 v38, v38, v57
	v_mul_f32_e32 v39, v39, v58
	v_mul_f32_e32 v40, v40, v59
	v_mul_f32_e32 v41, v41, v60
	v_cvt_pk_bf16_f32 v61, v38, v39
	v_cvt_pk_bf16_f32 v62, v40, v41
	v_add_u32_e32 v56, s98, v55
	global_store_short v55, v61, s[16:17]
	global_store_short_d16_hi v56, v61, s[16:17]
	v_add_u32_e32 v55, s98, v56
	v_add_u32_e32 v56, s98, v55
	global_store_short v55, v62, s[16:17]
	global_store_short_d16_hi v56, v62, s[16:17]
	v_add_u32_e32 v55, s99, v56
; __device__ __forceinline__ unsigned pk2(float lo, float hi) { unsigned r; asm volatile("v_cvt_pk_bf16_f32 %0, %1, %2" : "=v"(r) : "v"(lo), "v"(hi)); return r; }
; __device__ __forceinline__ void ph_filtergen(KP p, int l, unsigned char* sm, int wv) {
;     ...
;             for (int pp = 0; pp < 32; ++pp) {
;                 const f32x4* hr = (const f32x4*)(h2 + (ph0 + pp) * 68);
;                 float acc0 = 0.f, acc1 = 0.f;
; #pragma unroll
;                 for (int j4 = 0; j4 < 16; ++j4) { const f32x4 hv = hr[j4]; acc0 += hv.x * wcol[j4 * 4] + hv.z * wcol[j4 * 4 + 2]; acc1 += hv.y * wcol[j4 * 4 + 1] + hv.w * wcol[j4 * 4 + 3]; }
;                 ot[ol * 65 + ph0 + pp] = acc0 + acc1;
;             }
;             __syncthreads();
;             for (int e = tid; e < 256 * 64; e += 512) {
;                 const int ol2 = e >> 6, pos = e & 63, o2 = pass * 256 + ol2, c = o2 & 511, n = n0 + pos;
;                 const float tt = (float)n / (float)(L - 1);
;                 const float delta = fabsf(-3.070113457325394f + (float)c * ((-15.350567286626971f + 3.070113457325394f) / 511.0f));
;                 float val = ot[ol2 * 65 + pos] * __expf(-tt * delta);
;                 bf16_t* kc = kf + (size_t)c * (2 * L);
;                 if (o2 < 512) { if (n == 0) val += hb[c]; kc[n] = (bf16_t)(pk2(val, 0.f) & 0xffffu); }
	v_add_f32_e32 v57, 0x41800000, v54
	v_add_f32_e32 v58, 0x41880000, v54
	v_add_f32_e32 v59, 0x41900000, v54
	v_add_f32_e32 v60, 0x41980000, v54
	v_fmamk_f32 v57, v57, 0xbcc4df2d, v238
	v_fmamk_f32 v58, v58, 0xbcc4df2d, v238
	v_fmamk_f32 v59, v59, 0xbcc4df2d, v238
	v_fmamk_f32 v60, v60, 0xbcc4df2d, v238
	v_mul_f32_e64 v57, v52, |v57|
	v_mul_f32_e64 v58, v52, |v58|
	v_mul_f32_e64 v59, v52, |v59|
	v_mul_f32_e64 v60, v52, |v60|
	v_mul_f32_e32 v57, 0x3fb8aa3b, v57
	v_mul_f32_e32 v58, 0x3fb8aa3b, v58
	v_mul_f32_e32 v59, 0x3fb8aa3b, v59
	v_mul_f32_e32 v60, 0x3fb8aa3b, v60
	v_exp_f32_e32 v57, v57
	v_exp_f32_e32 v58, v58
	v_exp_f32_e32 v59, v59
	v_exp_f32_e32 v60, v60
	s_nop 0
	v_mul_f32_e32 v42, v42, v57
	v_mul_f32_e32 v43, v43, v58
	v_mul_f32_e32 v44, v44, v59
	v_mul_f32_e32 v45, v45, v60
	v_cvt_pk_bf16_f32 v61, v42, v43
	v_cvt_pk_bf16_f32 v62, v44, v45
	v_add_u32_e32 v56, s98, v55
	global_store_short v55, v61, s[16:17]
	global_store_short_d16_hi v56, v61, s[16:17]
	v_add_u32_e32 v55, s98, v56
	v_add_u32_e32 v56, s98, v55
	global_store_short v55, v62, s[16:17]
	global_store_short_d16_hi v56, v62, s[16:17]
	v_add_u32_e32 v55, s99, v56
	v_add_f32_e32 v57, 0x41c00000, v54
	v_add_f32_e32 v58, 0x41c80000, v54
	v_add_f32_e32 v59, 0x41d00000, v54
	v_add_f32_e32 v60, 0x41d80000, v54
	v_fmamk_f32 v57, v57, 0xbcc4df2d, v238
	v_fmamk_f32 v58, v58, 0xbcc4df2d, v238
	v_fmamk_f32 v59, v59, 0xbcc4df2d, v238
	v_fmamk_f32 v60, v60, 0xbcc4df2d, v238
	v_mul_f32_e64 v57, v52, |v57|
	v_mul_f32_e64 v58, v52, |v58|
	v_mul_f32_e64 v59, v52, |v59|
	v_mul_f32_e64 v60, v52, |v60|
	v_mul_f32_e32 v57, 0x3fb8aa3b, v57
	v_mul_f32_e32 v58, 0x3fb8aa3b, v58
	v_mul_f32_e32 v59, 0x3fb8aa3b, v59
	v_mul_f32_e32 v60, 0x3fb8aa3b, v60
	v_exp_f32_e32 v57, v57
	v_exp_f32_e32 v58, v58
	v_exp_f32_e32 v59, v59
	v_exp_f32_e32 v60, v60
	s_nop 0
	v_mul_f32_e32 v46, v46, v57
	v_mul_f32_e32 v47, v47, v58
	v_mul_f32_e32 v48, v48, v59
	v_mul_f32_e32 v49, v49, v60
	v_cvt_pk_bf16_f32 v61, v46, v47
	v_cvt_pk_bf16_f32 v62, v48, v49
	v_add_u32_e32 v56, s98, v55
	global_store_short v55, v61, s[16:17]
	global_store_short_d16_hi v56, v61, s[16:17]
	v_add_u32_e32 v55, s98, v56
	v_add_u32_e32 v56, s98, v55
	global_store_short v55, v62, s[16:17]
	global_store_short_d16_hi v56, v62, s[16:17]
	ds_read_b128 v[96:99], v129 offset:8704
	ds_read_b128 v[100:103], v129 offset:8720
	ds_read_b128 v[104:107], v129 offset:8736
	ds_read_b128 v[108:111], v129 offset:8752
	ds_read_b128 v[112:115], v129 offset:8768
	ds_read_b128 v[116:119], v129 offset:8784
	ds_read_b128 v[120:123], v129 offset:8800
	ds_read_b128 v[124:127], v129 offset:8816
	s_waitcnt lgkmcnt(0)
	v_mfma_f32_32x32x2_f32 v[34:49], v176, v96, 0
	v_mfma_f32_32x32x2_f32 v[34:49], v177, v97, v[34:49]
	v_mfma_f32_32x32x2_f32 v[34:49], v178, v98, v[34:49]
	v_mfma_f32_32x32x2_f32 v[34:49], v179, v99, v[34:49]
	v_mfma_f32_32x32x2_f32 v[34:49], v180, v100, v[34:49]
	v_mfma_f32_32x32x2_f32 v[34:49], v181, v101, v[34:49]
	v_mfma_f32_32x32x2_f32 v[34:49], v182, v102, v[34:49]
	v_mfma_f32_32x32x2_f32 v[34:49], v183, v103, v[34:49]
	v_mfma_f32_32x32x2_f32 v[34:49], v184, v104, v[34:49]
	v_mfma_f32_32x32x2_f32 v[34:49], v185, v105, v[34:49]
	v_mfma_f32_32x32x2_f32 v[34:49], v186, v106, v[34:49]
	v_mfma_f32_32x32x2_f32 v[34:49], v187, v107, v[34:49]
	v_mfma_f32_32x32x2_f32 v[34:49], v188, v108, v[34:49]
	v_mfma_f32_32x32x2_f32 v[34:49], v189, v109, v[34:49]
	v_mfma_f32_32x32x2_f32 v[34:49], v190, v110, v[34:49]
	v_mfma_f32_32x32x2_f32 v[34:49], v191, v111, v[34:49]
	v_mfma_f32_32x32x2_f32 v[34:49], v192, v112, v[34:49]
	v_mfma_f32_32x32x2_f32 v[34:49], v193, v113, v[34:49]
	v_mfma_f32_32x32x2_f32 v[34:49], v194, v114, v[34:49]
	v_mfma_f32_32x32x2_f32 v[34:49], v195, v115, v[34:49]
	v_mfma_f32_32x32x2_f32 v[34:49], v196, v116, v[34:49]
	v_mfma_f32_32x32x2_f32 v[34:49], v197, v117, v[34:49]
	v_mfma_f32_32x32x2_f32 v[34:49], v198, v118, v[34:49]
	v_mfma_f32_32x32x2_f32 v[34:49], v199, v119, v[34:49]
	v_mfma_f32_32x32x2_f32 v[34:49], v200, v120, v[34:49]
	v_mfma_f32_32x32x2_f32 v[34:49], v201, v121, v[34:49]
	v_mfma_f32_32x32x2_f32 v[34:49], v202, v122, v[34:49]
	v_mfma_f32_32x32x2_f32 v[34:49], v203, v123, v[34:49]
	v_mfma_f32_32x32x2_f32 v[34:49], v206, v124, v[34:49]
	v_mfma_f32_32x32x2_f32 v[34:49], v207, v125, v[34:49]
	v_mfma_f32_32x32x2_f32 v[34:49], v208, v126, v[34:49]
	v_mfma_f32_32x32x2_f32 v[34:49], v209, v127, v[34:49]
	v_lshlrev_b32_e32 v63, 2, v132
	v_add_u32_e32 v63, 0x80, v63
	ds_bpermute_b32 v52, v63, v94
	v_sub_u32_e32 v50, 1, v131
	v_lshl_add_u32 v50, v50, 5, v32
	s_lshl_b32 s98, 1, s42
	v_mov_b32_e32 v51, v50
	s_cmpk_lt_u32 s43, 0x200
	s_cbranch_scc1 .Lmy_fg_fwd_e_1
	v_sub_u32_e32 v51, s98, v50
; __device__ __forceinline__ unsigned pk2(float lo, float hi) { unsigned r; asm volatile("v_cvt_pk_bf16_f32 %0, %1, %2" : "=v"(r) : "v"(lo), "v"(hi)); return r; }
; __device__ __forceinline__ void ph_filtergen(KP p, int l, unsigned char* sm, int wv) {
;     ...
;             for (int e = tid; e < 256 * 64; e += 512) {
;                 const int ol2 = e >> 6, pos = e & 63, o2 = pass * 256 + ol2, c = o2 & 511, n = n0 + pos;
;                 const float tt = (float)n / (float)(L - 1);
;                 const float delta = fabsf(-3.070113457325394f + (float)c * ((-15.350567286626971f + 3.070113457325394f) / 511.0f));
;                 float val = ot[ol2 * 65 + pos] * __expf(-tt * delta);
;                 bf16_t* kc = kf + (size_t)c * (2 * L);
;                 if (o2 < 512) { if (n == 0) val += hb[c]; kc[n] = (bf16_t)(pk2(val, 0.f) & 0xffffu); }
.Lmy_fg_fwd_e_1:
	s_and_b32 s99, s43, 0x1ff
	v_lshl_add_u32 v64, v128, 5, s99
	v_lshl_add_u32 v64, v131, 2, v64
	v_cvt_f32_u32_e32 v54, v64
	s_add_i32 s99, s42, 1
	v_lshlrev_b32_e32 v53, s99, v64
	v_lshl_add_u32 v55, v51, 1, v53
	s_lshl_b32 s98, 2, s42
	s_mul_i32 s99, s98, 5
	s_nop 15
	s_nop 3
	s_waitcnt lgkmcnt(0)
	v_add_f32_e32 v57, 0x00000000, v54
	v_add_f32_e32 v58, 0x3f800000, v54
	v_add_f32_e32 v59, 0x40000000, v54
	v_add_f32_e32 v60, 0x40400000, v54
	v_fmamk_f32 v57, v57, 0xbcc4df2d, v238
	v_fmamk_f32 v58, v58, 0xbcc4df2d, v238
	v_fmamk_f32 v59, v59, 0xbcc4df2d, v238
	v_fmamk_f32 v60, v60, 0xbcc4df2d, v238
	v_mul_f32_e64 v57, v52, |v57|
	v_mul_f32_e64 v58, v52, |v58|
	v_mul_f32_e64 v59, v52, |v59|
	v_mul_f32_e64 v60, v52, |v60|
	v_mul_f32_e32 v57, 0x3fb8aa3b, v57
	v_mul_f32_e32 v58, 0x3fb8aa3b, v58
	v_mul_f32_e32 v59, 0x3fb8aa3b, v59
	v_mul_f32_e32 v60, 0x3fb8aa3b, v60
	v_exp_f32_e32 v57, v57
	v_exp_f32_e32 v58, v58
	v_exp_f32_e32 v59, v59
	v_exp_f32_e32 v60, v60
	s_nop 0
	v_mul_f32_e32 v34, v34, v57
	v_mul_f32_e32 v35, v35, v58
	v_mul_f32_e32 v36, v36, v59
	v_mul_f32_e32 v37, v37, v60
	v_cvt_pk_bf16_f32 v61, v34, v35
	v_cvt_pk_bf16_f32 v62, v36, v37
	v_add_u32_e32 v56, s98, v55
	global_store_short v55, v61, s[16:17]
	global_store_short_d16_hi v56, v61, s[16:17]
	v_add_u32_e32 v55, s98, v56
	v_add_u32_e32 v56, s98, v55
	global_store_short v55, v62, s[16:17]
	global_store_short_d16_hi v56, v62, s[16:17]
	v_add_u32_e32 v55, s99, v56
	v_add_f32_e32 v57, 0x41000000, v54
	v_add_f32_e32 v58, 0x41100000, v54
	v_add_f32_e32 v59, 0x41200000, v54
	v_add_f32_e32 v60, 0x41300000, v54
	v_fmamk_f32 v57, v57, 0xbcc4df2d, v238
	v_fmamk_f32 v58, v58, 0xbcc4df2d, v238
	v_fmamk_f32 v59, v59, 0xbcc4df2d, v238
	v_fmamk_f32 v60, v60, 0xbcc4df2d, v238
	v_mul_f32_e64 v57, v52, |v57|
	v_mul_f32_e64 v58, v52, |v58|
	v_mul_f32_e64 v59, v52, |v59|
	v_mul_f32_e64 v60, v52, |v60|
	v_mul_f32_e32 v57, 0x3fb8aa3b, v57
	v_mul_f32_e32 v58, 0x3fb8aa3b, v58
	v_mul_f32_e32 v59, 0x3fb8aa3b, v59
	v_mul_f32_e32 v60, 0x3fb8aa3b, v60
	v_exp_f32_e32 v57, v57
	v_exp_f32_e32 v58, v58
	v_exp_f32_e32 v59, v59
	v_exp_f32_e32 v60, v60
	s_nop 0
	v_mul_f32_e32 v38, v38, v57
	v_mul_f32_e32 v39, v39, v58
	v_mul_f32_e32 v40, v40, v59
	v_mul_f32_e32 v41, v41, v60
	v_cvt_pk_bf16_f32 v61, v38, v39
	v_cvt_pk_bf16_f32 v62, v40, v41
	v_add_u32_e32 v56, s98, v55
	global_store_short v55, v61, s[16:17]
	global_store_short_d16_hi v56, v61, s[16:17]
	v_add_u32_e32 v55, s98, v56
	v_add_u32_e32 v56, s98, v55
	global_store_short v55, v62, s[16:17]
	global_store_short_d16_hi v56, v62, s[16:17]
	v_add_u32_e32 v55, s99, v56
	v_add_f32_e32 v57, 0x41800000, v54
	v_add_f32_e32 v58, 0x41880000, v54
	v_add_f32_e32 v59, 0x41900000, v54
	v_add_f32_e32 v60, 0x41980000, v54
	v_fmamk_f32 v57, v57, 0xbcc4df2d, v238
	v_fmamk_f32 v58, v58, 0xbcc4df2d, v238
	v_fmamk_f32 v59, v59, 0xbcc4df2d, v238
	v_fmamk_f32 v60, v60, 0xbcc4df2d, v238
	v_mul_f32_e64 v57, v52, |v57|
	v_mul_f32_e64 v58, v52, |v58|
	v_mul_f32_e64 v59, v52, |v59|
	v_mul_f32_e64 v60, v52, |v60|
	v_mul_f32_e32 v57, 0x3fb8aa3b, v57
	v_mul_f32_e32 v58, 0x3fb8aa3b, v58
	v_mul_f32_e32 v59, 0x3fb8aa3b, v59
	v_mul_f32_e32 v60, 0x3fb8aa3b, v60
	v_exp_f32_e32 v57, v57
	v_exp_f32_e32 v58, v58
	v_exp_f32_e32 v59, v59
	v_exp_f32_e32 v60, v60
	s_nop 0
	v_mul_f32_e32 v42, v42, v57
	v_mul_f32_e32 v43, v43, v58
	v_mul_f32_e32 v44, v44, v59
	v_mul_f32_e32 v45, v45, v60
	v_cvt_pk_bf16_f32 v61, v42, v43
	v_cvt_pk_bf16_f32 v62, v44, v45
	v_add_u32_e32 v56, s98, v55
	global_store_short v55, v61, s[16:17]
	global_store_short_d16_hi v56, v61, s[16:17]
	v_add_u32_e32 v55, s98, v56
	v_add_u32_e32 v56, s98, v55
	global_store_short v55, v62, s[16:17]
	global_store_short_d16_hi v56, v62, s[16:17]
	v_add_u32_e32 v55, s99, v56
	v_add_f32_e32 v57, 0x41c00000, v54
	v_add_f32_e32 v58, 0x41c80000, v54
	v_add_f32_e32 v59, 0x41d00000, v54
	v_add_f32_e32 v60, 0x41d80000, v54
	v_fmamk_f32 v57, v57, 0xbcc4df2d, v238
	v_fmamk_f32 v58, v58, 0xbcc4df2d, v238
	v_fmamk_f32 v59, v59, 0xbcc4df2d, v238
	v_fmamk_f32 v60, v60, 0xbcc4df2d, v238
	v_mul_f32_e64 v57, v52, |v57|
	v_mul_f32_e64 v58, v52, |v58|
	v_mul_f32_e64 v59, v52, |v59|
	v_mul_f32_e64 v60, v52, |v60|
	v_mul_f32_e32 v57, 0x3fb8aa3b, v57
	v_mul_f32_e32 v58, 0x3fb8aa3b, v58
	v_mul_f32_e32 v59, 0x3fb8aa3b, v59
	v_mul_f32_e32 v60, 0x3fb8aa3b, v60
	v_exp_f32_e32 v57, v57
	v_exp_f32_e32 v58, v58
	v_exp_f32_e32 v59, v59
	v_exp_f32_e32 v60, v60
	s_nop 0
	v_mul_f32_e32 v46, v46, v57
	v_mul_f32_e32 v47, v47, v58
	v_mul_f32_e32 v48, v48, v59
	v_mul_f32_e32 v49, v49, v60
	v_cvt_pk_bf16_f32 v61, v46, v47
	v_cvt_pk_bf16_f32 v62, v48, v49
	v_add_u32_e32 v56, s98, v55
	global_store_short v55, v61, s[16:17]
	global_store_short_d16_hi v56, v61, s[16:17]
	v_add_u32_e32 v55, s98, v56
	v_add_u32_e32 v56, s98, v55
	global_store_short v55, v62, s[16:17]
	global_store_short_d16_hi v56, v62, s[16:17]
	s_branch .Lmy_fg_latch
; __device__ __forceinline__ void ph_filtergen(KP p, int l, unsigned char* sm, int wv) {
;     ...
;             for (int j = 0; j < 64; ++j) wcol[j] = w3[j * 1024 + o];
; #pragma unroll 2
;             for (int pp = 0; pp < 32; ++pp) {
;                 const f32x4* hr = (const f32x4*)(h2 + (ph0 + pp) * 68);
;                 float acc0 = 0.f, acc1 = 0.f;
; #pragma unroll
;                 for (int j4 = 0; j4 < 16; ++j4) { const f32x4 hv = hr[j4]; acc0 += hv.x * wcol[j4 * 4] + hv.z * wcol[j4 * 4 + 2]; acc1 += hv.y * wcol[j4 * 4 + 1] + hv.w * wcol[j4 * 4 + 3]; }
;                 ot[ol * 65 + ph0 + pp] = acc0 + acc1;
;             }
;             __syncthreads();
;             for (int e = tid; e < 256 * 64; e += 512) {
;                 const int ol2 = e >> 6, pos = e & 63, o2 = pass * 256 + ol2, c = o2 & 511, n = n0 + pos;
;                 const float tt = (float)n / (float)(L - 1);
;                 const float delta = fabsf(-3.070113457325394f + (float)c * ((-15.350567286626971f + 3.070113457325394f) / 511.0f));
;                 float val = ot[ol2 * 65 + pos] * __expf(-tt * delta);
.Lmy_fg_fast_odd:
	ds_read_b128 v[96:99], v129 offset:0
	ds_read_b128 v[100:103], v129 offset:16
	ds_read_b128 v[104:107], v129 offset:32
	ds_read_b128 v[108:111], v129 offset:48
	ds_read_b128 v[112:115], v129 offset:64
	ds_read_b128 v[116:119], v129 offset:80
	ds_read_b128 v[120:123], v129 offset:96
	ds_read_b128 v[124:127], v129 offset:112
	s_waitcnt lgkmcnt(0)
	v_mfma_f32_32x32x2_f32 v[34:49], v210, v96, 0
	v_mfma_f32_32x32x2_f32 v[34:49], v211, v97, v[34:49]
	v_mfma_f32_32x32x2_f32 v[34:49], v212, v98, v[34:49]
	v_mfma_f32_32x32x2_f32 v[34:49], v213, v99, v[34:49]
	v_mfma_f32_32x32x2_f32 v[34:49], v214, v100, v[34:49]
	v_mfma_f32_32x32x2_f32 v[34:49], v215, v101, v[34:49]
	v_mfma_f32_32x32x2_f32 v[34:49], v216, v102, v[34:49]
	v_mfma_f32_32x32x2_f32 v[34:49], v217, v103, v[34:49]
	v_mfma_f32_32x32x2_f32 v[34:49], v218, v104, v[34:49]
	v_mfma_f32_32x32x2_f32 v[34:49], v219, v105, v[34:49]
	v_mfma_f32_32x32x2_f32 v[34:49], v220, v106, v[34:49]
	v_mfma_f32_32x32x2_f32 v[34:49], v221, v107, v[34:49]
	v_mfma_f32_32x32x2_f32 v[34:49], v222, v108, v[34:49]
	v_mfma_f32_32x32x2_f32 v[34:49], v223, v109, v[34:49]
	v_mfma_f32_32x32x2_f32 v[34:49], v224, v110, v[34:49]
	v_mfma_f32_32x32x2_f32 v[34:49], v225, v111, v[34:49]
	v_mfma_f32_32x32x2_f32 v[34:49], v226, v112, v[34:49]
	v_mfma_f32_32x32x2_f32 v[34:49], v227, v113, v[34:49]
	v_mfma_f32_32x32x2_f32 v[34:49], v228, v114, v[34:49]
	v_mfma_f32_32x32x2_f32 v[34:49], v229, v115, v[34:49]
	v_mfma_f32_32x32x2_f32 v[34:49], v232, v116, v[34:49]
	v_mfma_f32_32x32x2_f32 v[34:49], v233, v117, v[34:49]
	v_mfma_f32_32x32x2_f32 v[34:49], v234, v118, v[34:49]
	v_mfma_f32_32x32x2_f32 v[34:49], v235, v119, v[34:49]
	v_mfma_f32_32x32x2_f32 v[34:49], v245, v120, v[34:49]
	v_mfma_f32_32x32x2_f32 v[34:49], v246, v121, v[34:49]
	v_mfma_f32_32x32x2_f32 v[34:49], v247, v122, v[34:49]
	v_mfma_f32_32x32x2_f32 v[34:49], v248, v123, v[34:49]
	v_mfma_f32_32x32x2_f32 v[34:49], v249, v124, v[34:49]
	v_mfma_f32_32x32x2_f32 v[34:49], v250, v125, v[34:49]
	v_mfma_f32_32x32x2_f32 v[34:49], v251, v126, v[34:49]
	v_mfma_f32_32x32x2_f32 v[34:49], v143, v127, v[34:49]
	v_lshlrev_b32_e32 v63, 2, v132
	ds_bpermute_b32 v52, v63, v94
	v_sub_u32_e32 v50, 0, v131
	v_lshl_add_u32 v50, v50, 5, v32
	s_lshl_b32 s98, 1, s42
	v_mov_b32_e32 v51, v50
	s_cmpk_lt_u32 s43, 0x200
	s_cbranch_scc1 .Lmy_fg_fwd_o_0
	v_sub_u32_e32 v51, s98, v50
.Lmy_fg_fwd_o_0:
	s_and_b32 s99, s43, 0x1ff
	v_lshl_add_u32 v64, v128, 5, s99
	v_lshl_add_u32 v64, v131, 2, v64
	v_cvt_f32_u32_e32 v54, v64
	s_add_i32 s99, s42, 1
	v_lshlrev_b32_e32 v53, s99, v64
	v_lshl_add_u32 v55, v51, 1, v53
	s_lshl_b32 s98, 2, s42
	s_mul_i32 s99, s98, 5
	s_nop 15
	s_nop 3
	s_waitcnt lgkmcnt(0)
; __device__ __forceinline__ unsigned pk2(float lo, float hi) { unsigned r; asm volatile("v_cvt_pk_bf16_f32 %0, %1, %2" : "=v"(r) : "v"(lo), "v"(hi)); return r; }
; __device__ __forceinline__ void ph_filtergen(KP p, int l, unsigned char* sm, int wv) {
;     ...
;             for (int j = 0; j < 64; ++j) wcol[j] = w3[j * 1024 + o];
; #pragma unroll 2
;             for (int pp = 0; pp < 32; ++pp) {
;                 const f32x4* hr = (const f32x4*)(h2 + (ph0 + pp) * 68);
;                 float acc0 = 0.f, acc1 = 0.f;
; #pragma unroll
;                 for (int j4 = 0; j4 < 16; ++j4) { const f32x4 hv = hr[j4]; acc0 += hv.x * wcol[j4 * 4] + hv.z * wcol[j4 * 4 + 2]; acc1 += hv.y * wcol[j4 * 4 + 1] + hv.w * wcol[j4 * 4 + 3]; }
;                 ot[ol * 65 + ph0 + pp] = acc0 + acc1;
;             }
;             __syncthreads();
;             for (int e = tid; e < 256 * 64; e += 512) {
;                 const int ol2 = e >> 6, pos = e & 63, o2 = pass * 256 + ol2, c = o2 & 511, n = n0 + pos;
;                 const float tt = (float)n / (float)(L - 1);
;                 const float delta = fabsf(-3.070113457325394f + (float)c * ((-15.350567286626971f + 3.070113457325394f) / 511.0f));
;                 float val = ot[ol2 * 65 + pos] * __expf(-tt * delta);
;                 bf16_t* kc = kf + (size_t)c * (2 * L);
;                 if (o2 < 512) { if (n == 0) val += hb[c]; kc[n] = (bf16_t)(pk2(val, 0.f) & 0xffffu); }
	v_add_f32_e32 v57, 0x00000000, v54
	v_add_f32_e32 v58, 0x3f800000, v54
	v_add_f32_e32 v59, 0x40000000, v54
	v_add_f32_e32 v60, 0x40400000, v54
	v_fmamk_f32 v57, v57, 0xbcc4df2d, v238
	v_fmamk_f32 v58, v58, 0xbcc4df2d, v238
	v_fmamk_f32 v59, v59, 0xbcc4df2d, v238
	v_fmamk_f32 v60, v60, 0xbcc4df2d, v238
	v_mul_f32_e64 v57, v52, |v57|
	v_mul_f32_e64 v58, v52, |v58|
	v_mul_f32_e64 v59, v52, |v59|
	v_mul_f32_e64 v60, v52, |v60|
	v_mul_f32_e32 v57, 0x3fb8aa3b, v57
	v_mul_f32_e32 v58, 0x3fb8aa3b, v58
	v_mul_f32_e32 v59, 0x3fb8aa3b, v59
	v_mul_f32_e32 v60, 0x3fb8aa3b, v60
	v_exp_f32_e32 v57, v57
	v_exp_f32_e32 v58, v58
	v_exp_f32_e32 v59, v59
	v_exp_f32_e32 v60, v60
	s_nop 0
	v_mul_f32_e32 v34, v34, v57
	v_mul_f32_e32 v35, v35, v58
	v_mul_f32_e32 v36, v36, v59
	v_mul_f32_e32 v37, v37, v60
	v_cvt_pk_bf16_f32 v61, v34, v35
	v_cvt_pk_bf16_f32 v62, v36, v37
	v_add_u32_e32 v56, s98, v55
	global_store_short v55, v61, s[16:17]
	global_store_short_d16_hi v56, v61, s[16:17]
	v_add_u32_e32 v55, s98, v56
	v_add_u32_e32 v56, s98, v55
	global_store_short v55, v62, s[16:17]
	global_store_short_d16_hi v56, v62, s[16:17]
	v_add_u32_e32 v55, s99, v56
	v_add_f32_e32 v57, 0x41000000, v54
	v_add_f32_e32 v58, 0x41100000, v54
	v_add_f32_e32 v59, 0x41200000, v54
	v_add_f32_e32 v60, 0x41300000, v54
	v_fmamk_f32 v57, v57, 0xbcc4df2d, v238
	v_fmamk_f32 v58, v58, 0xbcc4df2d, v238
	v_fmamk_f32 v59, v59, 0xbcc4df2d, v238
	v_fmamk_f32 v60, v60, 0xbcc4df2d, v238
	v_mul_f32_e64 v57, v52, |v57|
	v_mul_f32_e64 v58, v52, |v58|
	v_mul_f32_e64 v59, v52, |v59|
	v_mul_f32_e64 v60, v52, |v60|
	v_mul_f32_e32 v57, 0x3fb8aa3b, v57
	v_mul_f32_e32 v58, 0x3fb8aa3b, v58
	v_mul_f32_e32 v59, 0x3fb8aa3b, v59
	v_mul_f32_e32 v60, 0x3fb8aa3b, v60
	v_exp_f32_e32 v57, v57
	v_exp_f32_e32 v58, v58
	v_exp_f32_e32 v59, v59
	v_exp_f32_e32 v60, v60
	s_nop 0
	v_mul_f32_e32 v38, v38, v57
	v_mul_f32_e32 v39, v39, v58
	v_mul_f32_e32 v40, v40, v59
	v_mul_f32_e32 v41, v41, v60
	v_cvt_pk_bf16_f32 v61, v38, v39
	v_cvt_pk_bf16_f32 v62, v40, v41
	v_add_u32_e32 v56, s98, v55
	global_store_short v55, v61, s[16:17]
	global_store_short_d16_hi v56, v61, s[16:17]
	v_add_u32_e32 v55, s98, v56
	v_add_u32_e32 v56, s98, v55
	global_store_short v55, v62, s[16:17]
	global_store_short_d16_hi v56, v62, s[16:17]
	v_add_u32_e32 v55, s99, v56
	v_add_f32_e32 v57, 0x41800000, v54
	v_add_f32_e32 v58, 0x41880000, v54
	v_add_f32_e32 v59, 0x41900000, v54
	v_add_f32_e32 v60, 0x41980000, v54
	v_fmamk_f32 v57, v57, 0xbcc4df2d, v238
	v_fmamk_f32 v58, v58, 0xbcc4df2d, v238
	v_fmamk_f32 v59, v59, 0xbcc4df2d, v238
	v_fmamk_f32 v60, v60, 0xbcc4df2d, v238
	v_mul_f32_e64 v57, v52, |v57|
	v_mul_f32_e64 v58, v52, |v58|
	v_mul_f32_e64 v59, v52, |v59|
	v_mul_f32_e64 v60, v52, |v60|
	v_mul_f32_e32 v57, 0x3fb8aa3b, v57
	v_mul_f32_e32 v58, 0x3fb8aa3b, v58
	v_mul_f32_e32 v59, 0x3fb8aa3b, v59
	v_mul_f32_e32 v60, 0x3fb8aa3b, v60
	v_exp_f32_e32 v57, v57
	v_exp_f32_e32 v58, v58
	v_exp_f32_e32 v59, v59
	v_exp_f32_e32 v60, v60
	s_nop 0
	v_mul_f32_e32 v42, v42, v57
	v_mul_f32_e32 v43, v43, v58
	v_mul_f32_e32 v44, v44, v59
	v_mul_f32_e32 v45, v45, v60
	v_cvt_pk_bf16_f32 v61, v42, v43
	v_cvt_pk_bf16_f32 v62, v44, v45
	v_add_u32_e32 v56, s98, v55
	global_store_short v55, v61, s[16:17]
	global_store_short_d16_hi v56, v61, s[16:17]
	v_add_u32_e32 v55, s98, v56
	v_add_u32_e32 v56, s98, v55
	global_store_short v55, v62, s[16:17]
	global_store_short_d16_hi v56, v62, s[16:17]
	v_add_u32_e32 v55, s99, v56
	v_add_f32_e32 v57, 0x41c00000, v54
	v_add_f32_e32 v58, 0x41c80000, v54
	v_add_f32_e32 v59, 0x41d00000, v54
	v_add_f32_e32 v60, 0x41d80000, v54
	v_fmamk_f32 v57, v57, 0xbcc4df2d, v238
	v_fmamk_f32 v58, v58, 0xbcc4df2d, v238
	v_fmamk_f32 v59, v59, 0xbcc4df2d, v238
	v_fmamk_f32 v60, v60, 0xbcc4df2d, v238
	v_mul_f32_e64 v57, v52, |v57|
	v_mul_f32_e64 v58, v52, |v58|
	v_mul_f32_e64 v59, v52, |v59|
	v_mul_f32_e64 v60, v52, |v60|
	v_mul_f32_e32 v57, 0x3fb8aa3b, v57
	v_mul_f32_e32 v58, 0x3fb8aa3b, v58
	v_mul_f32_e32 v59, 0x3fb8aa3b, v59
	v_mul_f32_e32 v60, 0x3fb8aa3b, v60
	v_exp_f32_e32 v57, v57
	v_exp_f32_e32 v58, v58
	v_exp_f32_e32 v59, v59
	v_exp_f32_e32 v60, v60
	s_nop 0
	v_mul_f32_e32 v46, v46, v57
	v_mul_f32_e32 v47, v47, v58
	v_mul_f32_e32 v48, v48, v59
	v_mul_f32_e32 v49, v49, v60
	v_cvt_pk_bf16_f32 v61, v46, v47
	v_cvt_pk_bf16_f32 v62, v48, v49
	v_add_u32_e32 v56, s98, v55
	global_store_short v55, v61, s[16:17]
	global_store_short_d16_hi v56, v61, s[16:17]
	v_add_u32_e32 v55, s98, v56
	v_add_u32_e32 v56, s98, v55
	global_store_short v55, v62, s[16:17]
	global_store_short_d16_hi v56, v62, s[16:17]
	ds_read_b128 v[96:99], v129 offset:8704
	ds_read_b128 v[100:103], v129 offset:8720
	ds_read_b128 v[104:107], v129 offset:8736
	ds_read_b128 v[108:111], v129 offset:8752
	ds_read_b128 v[112:115], v129 offset:8768
	ds_read_b128 v[116:119], v129 offset:8784
	ds_read_b128 v[120:123], v129 offset:8800
	ds_read_b128 v[124:127], v129 offset:8816
	s_waitcnt lgkmcnt(0)
	v_mfma_f32_32x32x2_f32 v[34:49], v210, v96, 0
	v_mfma_f32_32x32x2_f32 v[34:49], v211, v97, v[34:49]
	v_mfma_f32_32x32x2_f32 v[34:49], v212, v98, v[34:49]
	v_mfma_f32_32x32x2_f32 v[34:49], v213, v99, v[34:49]
	v_mfma_f32_32x32x2_f32 v[34:49], v214, v100, v[34:49]
	v_mfma_f32_32x32x2_f32 v[34:49], v215, v101, v[34:49]
	v_mfma_f32_32x32x2_f32 v[34:49], v216, v102, v[34:49]
	v_mfma_f32_32x32x2_f32 v[34:49], v217, v103, v[34:49]
	v_mfma_f32_32x32x2_f32 v[34:49], v218, v104, v[34:49]
	v_mfma_f32_32x32x2_f32 v[34:49], v219, v105, v[34:49]
	v_mfma_f32_32x32x2_f32 v[34:49], v220, v106, v[34:49]
	v_mfma_f32_32x32x2_f32 v[34:49], v221, v107, v[34:49]
	v_mfma_f32_32x32x2_f32 v[34:49], v222, v108, v[34:49]
	v_mfma_f32_32x32x2_f32 v[34:49], v223, v109, v[34:49]
	v_mfma_f32_32x32x2_f32 v[34:49], v224, v110, v[34:49]
	v_mfma_f32_32x32x2_f32 v[34:49], v225, v111, v[34:49]
	v_mfma_f32_32x32x2_f32 v[34:49], v226, v112, v[34:49]
	v_mfma_f32_32x32x2_f32 v[34:49], v227, v113, v[34:49]
	v_mfma_f32_32x32x2_f32 v[34:49], v228, v114, v[34:49]
	v_mfma_f32_32x32x2_f32 v[34:49], v229, v115, v[34:49]
	v_mfma_f32_32x32x2_f32 v[34:49], v232, v116, v[34:49]
	v_mfma_f32_32x32x2_f32 v[34:49], v233, v117, v[34:49]
	v_mfma_f32_32x32x2_f32 v[34:49], v234, v118, v[34:49]
	v_mfma_f32_32x32x2_f32 v[34:49], v235, v119, v[34:49]
	v_mfma_f32_32x32x2_f32 v[34:49], v245, v120, v[34:49]
	v_mfma_f32_32x32x2_f32 v[34:49], v246, v121, v[34:49]
	v_mfma_f32_32x32x2_f32 v[34:49], v247, v122, v[34:49]
	v_mfma_f32_32x32x2_f32 v[34:49], v248, v123, v[34:49]
	v_mfma_f32_32x32x2_f32 v[34:49], v249, v124, v[34:49]
	v_mfma_f32_32x32x2_f32 v[34:49], v250, v125, v[34:49]
	v_mfma_f32_32x32x2_f32 v[34:49], v251, v126, v[34:49]
	v_mfma_f32_32x32x2_f32 v[34:49], v143, v127, v[34:49]
	v_lshlrev_b32_e32 v63, 2, v132
	v_add_u32_e32 v63, 0x80, v63
	ds_bpermute_b32 v52, v63, v94
	v_sub_u32_e32 v50, 1, v131
	v_lshl_add_u32 v50, v50, 5, v32
	s_lshl_b32 s98, 1, s42
	v_mov_b32_e32 v51, v50
	s_cmpk_lt_u32 s43, 0x200
	s_cbranch_scc1 .Lmy_fg_fwd_o_1
	v_sub_u32_e32 v51, s98, v50

; __device__ __forceinline__ void ph_filtergen(KP p, int l, unsigned char* sm, int wv) {
;     ...
;             for (int j = 0; j < 64; ++j) wcol[j] = w3[j * 1024 + o];
; #pragma unroll 2
;             for (int pp = 0; pp < 32; ++pp) {
;                 const f32x4* hr = (const f32x4*)(h2 + (ph0 + pp) * 68);
;                 float acc0 = 0.f, acc1 = 0.f;
; #pragma unroll
;                 for (int j4 = 0; j4 < 16; ++j4) { const f32x4 hv = hr[j4]; acc0 += hv.x * wcol[j4 * 4] + hv.z * wcol[j4 * 4 + 2]; acc1 += hv.y * wcol[j4 * 4 + 1] + hv.w * wcol[j4 * 4 + 3]; }
;                 ot[ol * 65 + ph0 + pp] = acc0 + acc1;
;             }
;             __syncthreads();
.Lmy_fg_slow:
	s_bitcmp1_b32 s31, 0
	s_cbranch_scc1 .Lmy_fg_odd
	ds_read_b128 v[96:99], v129 offset:0
	ds_read_b128 v[100:103], v129 offset:16
	ds_read_b128 v[104:107], v129 offset:32
	ds_read_b128 v[108:111], v129 offset:48
	ds_read_b128 v[112:115], v129 offset:64
	ds_read_b128 v[116:119], v129 offset:80
	ds_read_b128 v[120:123], v129 offset:96
	ds_read_b128 v[124:127], v129 offset:112
	s_waitcnt vmcnt(0) lgkmcnt(0)
	v_mfma_f32_32x32x2_f32 v[34:49], v176, v96, 0
	v_mfma_f32_32x32x2_f32 v[34:49], v177, v97, v[34:49]
	v_mfma_f32_32x32x2_f32 v[34:49], v178, v98, v[34:49]
	v_mfma_f32_32x32x2_f32 v[34:49], v179, v99, v[34:49]
	v_mfma_f32_32x32x2_f32 v[34:49], v180, v100, v[34:49]
	v_mfma_f32_32x32x2_f32 v[34:49], v181, v101, v[34:49]
	v_mfma_f32_32x32x2_f32 v[34:49], v182, v102, v[34:49]
	v_mfma_f32_32x32x2_f32 v[34:49], v183, v103, v[34:49]
	v_mfma_f32_32x32x2_f32 v[34:49], v184, v104, v[34:49]
	v_mfma_f32_32x32x2_f32 v[34:49], v185, v105, v[34:49]
	v_mfma_f32_32x32x2_f32 v[34:49], v186, v106, v[34:49]
	v_mfma_f32_32x32x2_f32 v[34:49], v187, v107, v[34:49]
	v_mfma_f32_32x32x2_f32 v[34:49], v188, v108, v[34:49]
	v_mfma_f32_32x32x2_f32 v[34:49], v189, v109, v[34:49]
	v_mfma_f32_32x32x2_f32 v[34:49], v190, v110, v[34:49]
	v_mfma_f32_32x32x2_f32 v[34:49], v191, v111, v[34:49]
	v_mfma_f32_32x32x2_f32 v[34:49], v192, v112, v[34:49]
	v_mfma_f32_32x32x2_f32 v[34:49], v193, v113, v[34:49]
	v_mfma_f32_32x32x2_f32 v[34:49], v194, v114, v[34:49]
	v_mfma_f32_32x32x2_f32 v[34:49], v195, v115, v[34:49]
	v_mfma_f32_32x32x2_f32 v[34:49], v196, v116, v[34:49]
	v_mfma_f32_32x32x2_f32 v[34:49], v197, v117, v[34:49]
	v_mfma_f32_32x32x2_f32 v[34:49], v198, v118, v[34:49]
	v_mfma_f32_32x32x2_f32 v[34:49], v199, v119, v[34:49]
	v_mfma_f32_32x32x2_f32 v[34:49], v200, v120, v[34:49]
	v_mfma_f32_32x32x2_f32 v[34:49], v201, v121, v[34:49]
	v_mfma_f32_32x32x2_f32 v[34:49], v202, v122, v[34:49]
	v_mfma_f32_32x32x2_f32 v[34:49], v203, v123, v[34:49]
	v_mfma_f32_32x32x2_f32 v[34:49], v206, v124, v[34:49]
	v_mfma_f32_32x32x2_f32 v[34:49], v207, v125, v[34:49]
	v_mfma_f32_32x32x2_f32 v[34:49], v208, v126, v[34:49]
	v_mfma_f32_32x32x2_f32 v[34:49], v209, v127, v[34:49]
	s_nop 15
	s_nop 3
	ds_write_b32 v130, v34 offset:0
	ds_write_b32 v130, v35 offset:260
	ds_write_b32 v130, v36 offset:520
	ds_write_b32 v130, v37 offset:780
	ds_write_b32 v130, v38 offset:2080
	ds_write_b32 v130, v39 offset:2340
	ds_write_b32 v130, v40 offset:2600
	ds_write_b32 v130, v41 offset:2860
	ds_write_b32 v130, v42 offset:4160
	ds_write_b32 v130, v43 offset:4420
	ds_write_b32 v130, v44 offset:4680
	ds_write_b32 v130, v45 offset:4940
	ds_write_b32 v130, v46 offset:6240
	ds_write_b32 v130, v47 offset:6500
	ds_write_b32 v130, v48 offset:6760
	ds_write_b32 v130, v49 offset:7020
	ds_read_b128 v[96:99], v129 offset:8704
	ds_read_b128 v[100:103], v129 offset:8720
	ds_read_b128 v[104:107], v129 offset:8736
	ds_read_b128 v[108:111], v129 offset:8752
	ds_read_b128 v[112:115], v129 offset:8768
	ds_read_b128 v[116:119], v129 offset:8784
	ds_read_b128 v[120:123], v129 offset:8800
	ds_read_b128 v[124:127], v129 offset:8816
	s_waitcnt lgkmcnt(0)
	v_mfma_f32_32x32x2_f32 v[34:49], v176, v96, 0
	v_mfma_f32_32x32x2_f32 v[34:49], v177, v97, v[34:49]
	v_mfma_f32_32x32x2_f32 v[34:49], v178, v98, v[34:49]
	v_mfma_f32_32x32x2_f32 v[34:49], v179, v99, v[34:49]
	v_mfma_f32_32x32x2_f32 v[34:49], v180, v100, v[34:49]
	v_mfma_f32_32x32x2_f32 v[34:49], v181, v101, v[34:49]
	v_mfma_f32_32x32x2_f32 v[34:49], v182, v102, v[34:49]
	v_mfma_f32_32x32x2_f32 v[34:49], v183, v103, v[34:49]
	v_mfma_f32_32x32x2_f32 v[34:49], v184, v104, v[34:49]
	v_mfma_f32_32x32x2_f32 v[34:49], v185, v105, v[34:49]
	v_mfma_f32_32x32x2_f32 v[34:49], v186, v106, v[34:49]
	v_mfma_f32_32x32x2_f32 v[34:49], v187, v107, v[34:49]
	v_mfma_f32_32x32x2_f32 v[34:49], v188, v108, v[34:49]
	v_mfma_f32_32x32x2_f32 v[34:49], v189, v109, v[34:49]
	v_mfma_f32_32x32x2_f32 v[34:49], v190, v110, v[34:49]
	v_mfma_f32_32x32x2_f32 v[34:49], v191, v111, v[34:49]
	v_mfma_f32_32x32x2_f32 v[34:49], v192, v112, v[34:49]
	v_mfma_f32_32x32x2_f32 v[34:49], v193, v113, v[34:49]
	v_mfma_f32_32x32x2_f32 v[34:49], v194, v114, v[34:49]
	v_mfma_f32_32x32x2_f32 v[34:49], v195, v115, v[34:49]
	v_mfma_f32_32x32x2_f32 v[34:49], v196, v116, v[34:49]
	v_mfma_f32_32x32x2_f32 v[34:49], v197, v117, v[34:49]
	v_mfma_f32_32x32x2_f32 v[34:49], v198, v118, v[34:49]
	v_mfma_f32_32x32x2_f32 v[34:49], v199, v119, v[34:49]
	v_mfma_f32_32x32x2_f32 v[34:49], v200, v120, v[34:49]
	v_mfma_f32_32x32x2_f32 v[34:49], v201, v121, v[34:49]
	v_mfma_f32_32x32x2_f32 v[34:49], v202, v122, v[34:49]
	v_mfma_f32_32x32x2_f32 v[34:49], v203, v123, v[34:49]
	v_mfma_f32_32x32x2_f32 v[34:49], v206, v124, v[34:49]
	v_mfma_f32_32x32x2_f32 v[34:49], v207, v125, v[34:49]
	v_mfma_f32_32x32x2_f32 v[34:49], v208, v126, v[34:49]
	v_mfma_f32_32x32x2_f32 v[34:49], v209, v127, v[34:49]
	s_nop 15
	s_nop 3
	ds_write_b32 v130, v34 offset:128
	ds_write_b32 v130, v35 offset:388
	ds_write_b32 v130, v36 offset:648
	ds_write_b32 v130, v37 offset:908
	ds_write_b32 v130, v38 offset:2208
	ds_write_b32 v130, v39 offset:2468
	ds_write_b32 v130, v40 offset:2728
	ds_write_b32 v130, v41 offset:2988
	ds_write_b32 v130, v42 offset:4288
	ds_write_b32 v130, v43 offset:4548
	ds_write_b32 v130, v44 offset:4808
	ds_write_b32 v130, v45 offset:5068
	ds_write_b32 v130, v46 offset:6368
	ds_write_b32 v130, v47 offset:6628
	ds_write_b32 v130, v48 offset:6888
	ds_write_b32 v130, v49 offset:7148
	s_branch .Lmy_fg_join
; __device__ __forceinline__ void ph_filtergen(KP p, int l, unsigned char* sm, int wv) {
;     ...
;             for (int j = 0; j < 64; ++j) wcol[j] = w3[j * 1024 + o];
; #pragma unroll 2
;             for (int pp = 0; pp < 32; ++pp) {
;                 const f32x4* hr = (const f32x4*)(h2 + (ph0 + pp) * 68);
;                 float acc0 = 0.f, acc1 = 0.f;
; #pragma unroll
;                 for (int j4 = 0; j4 < 16; ++j4) { const f32x4 hv = hr[j4]; acc0 += hv.x * wcol[j4 * 4] + hv.z * wcol[j4 * 4 + 2]; acc1 += hv.y * wcol[j4 * 4 + 1] + hv.w * wcol[j4 * 4 + 3]; }
;                 ot[ol * 65 + ph0 + pp] = acc0 + acc1;
;             }
;             __syncthreads();
;             for (int e = tid; e < 256 * 64; e += 512) {
.Lmy_fg_odd:
	ds_read_b128 v[96:99], v129 offset:0
	ds_read_b128 v[100:103], v129 offset:16
	ds_read_b128 v[104:107], v129 offset:32
	ds_read_b128 v[108:111], v129 offset:48
	ds_read_b128 v[112:115], v129 offset:64
	ds_read_b128 v[116:119], v129 offset:80
	ds_read_b128 v[120:123], v129 offset:96
	ds_read_b128 v[124:127], v129 offset:112
	s_waitcnt vmcnt(0) lgkmcnt(0)
	v_mfma_f32_32x32x2_f32 v[34:49], v210, v96, 0
	v_mfma_f32_32x32x2_f32 v[34:49], v211, v97, v[34:49]
	v_mfma_f32_32x32x2_f32 v[34:49], v212, v98, v[34:49]
	v_mfma_f32_32x32x2_f32 v[34:49], v213, v99, v[34:49]
	v_mfma_f32_32x32x2_f32 v[34:49], v214, v100, v[34:49]
	v_mfma_f32_32x32x2_f32 v[34:49], v215, v101, v[34:49]
	v_mfma_f32_32x32x2_f32 v[34:49], v216, v102, v[34:49]
	v_mfma_f32_32x32x2_f32 v[34:49], v217, v103, v[34:49]
	v_mfma_f32_32x32x2_f32 v[34:49], v218, v104, v[34:49]
	v_mfma_f32_32x32x2_f32 v[34:49], v219, v105, v[34:49]
	v_mfma_f32_32x32x2_f32 v[34:49], v220, v106, v[34:49]
	v_mfma_f32_32x32x2_f32 v[34:49], v221, v107, v[34:49]
	v_mfma_f32_32x32x2_f32 v[34:49], v222, v108, v[34:49]
	v_mfma_f32_32x32x2_f32 v[34:49], v223, v109, v[34:49]
	v_mfma_f32_32x32x2_f32 v[34:49], v224, v110, v[34:49]
	v_mfma_f32_32x32x2_f32 v[34:49], v225, v111, v[34:49]
	v_mfma_f32_32x32x2_f32 v[34:49], v226, v112, v[34:49]
	v_mfma_f32_32x32x2_f32 v[34:49], v227, v113, v[34:49]
	v_mfma_f32_32x32x2_f32 v[34:49], v228, v114, v[34:49]
	v_mfma_f32_32x32x2_f32 v[34:49], v229, v115, v[34:49]
	v_mfma_f32_32x32x2_f32 v[34:49], v232, v116, v[34:49]
	v_mfma_f32_32x32x2_f32 v[34:49], v233, v117, v[34:49]
	v_mfma_f32_32x32x2_f32 v[34:49], v234, v118, v[34:49]
	v_mfma_f32_32x32x2_f32 v[34:49], v235, v119, v[34:49]
	v_mfma_f32_32x32x2_f32 v[34:49], v245, v120, v[34:49]
	v_mfma_f32_32x32x2_f32 v[34:49], v246, v121, v[34:49]
	v_mfma_f32_32x32x2_f32 v[34:49], v247, v122, v[34:49]
	v_mfma_f32_32x32x2_f32 v[34:49], v248, v123, v[34:49]
	v_mfma_f32_32x32x2_f32 v[34:49], v249, v124, v[34:49]
	v_mfma_f32_32x32x2_f32 v[34:49], v250, v125, v[34:49]
	v_mfma_f32_32x32x2_f32 v[34:49], v251, v126, v[34:49]
	v_mfma_f32_32x32x2_f32 v[34:49], v143, v127, v[34:49]
	s_nop 15
	s_nop 3
	ds_write_b32 v130, v34 offset:0
	ds_write_b32 v130, v35 offset:260
	ds_write_b32 v130, v36 offset:520
	ds_write_b32 v130, v37 offset:780
	ds_write_b32 v130, v38 offset:2080
	ds_write_b32 v130, v39 offset:2340
	ds_write_b32 v130, v40 offset:2600
	ds_write_b32 v130, v41 offset:2860
	ds_write_b32 v130, v42 offset:4160
	ds_write_b32 v130, v43 offset:4420
	ds_write_b32 v130, v44 offset:4680
	ds_write_b32 v130, v45 offset:4940
	ds_write_b32 v130, v46 offset:6240
	ds_write_b32 v130, v47 offset:6500
	ds_write_b32 v130, v48 offset:6760
	ds_write_b32 v130, v49 offset:7020
	ds_read_b128 v[96:99], v129 offset:8704
	ds_read_b128 v[100:103], v129 offset:8720
	ds_read_b128 v[104:107], v129 offset:8736
	ds_read_b128 v[108:111], v129 offset:8752
	ds_read_b128 v[112:115], v129 offset:8768
	ds_read_b128 v[116:119], v129 offset:8784
	ds_read_b128 v[120:123], v129 offset:8800
	ds_read_b128 v[124:127], v129 offset:8816
	s_waitcnt lgkmcnt(0)
	v_mfma_f32_32x32x2_f32 v[34:49], v210, v96, 0
	v_mfma_f32_32x32x2_f32 v[34:49], v211, v97, v[34:49]
	v_mfma_f32_32x32x2_f32 v[34:49], v212, v98, v[34:49]
	v_mfma_f32_32x32x2_f32 v[34:49], v213, v99, v[34:49]
	v_mfma_f32_32x32x2_f32 v[34:49], v214, v100, v[34:49]
	v_mfma_f32_32x32x2_f32 v[34:49], v215, v101, v[34:49]
	v_mfma_f32_32x32x2_f32 v[34:49], v216, v102, v[34:49]
	v_mfma_f32_32x32x2_f32 v[34:49], v217, v103, v[34:49]
	v_mfma_f32_32x32x2_f32 v[34:49], v218, v104, v[34:49]
	v_mfma_f32_32x32x2_f32 v[34:49], v219, v105, v[34:49]
	v_mfma_f32_32x32x2_f32 v[34:49], v220, v106, v[34:49]
	v_mfma_f32_32x32x2_f32 v[34:49], v221, v107, v[34:49]
	v_mfma_f32_32x32x2_f32 v[34:49], v222, v108, v[34:49]
	v_mfma_f32_32x32x2_f32 v[34:49], v223, v109, v[34:49]
	v_mfma_f32_32x32x2_f32 v[34:49], v224, v110, v[34:49]
	v_mfma_f32_32x32x2_f32 v[34:49], v225, v111, v[34:49]
	v_mfma_f32_32x32x2_f32 v[34:49], v226, v112, v[34:49]
	v_mfma_f32_32x32x2_f32 v[34:49], v227, v113, v[34:49]
	v_mfma_f32_32x32x2_f32 v[34:49], v228, v114, v[34:49]
	v_mfma_f32_32x32x2_f32 v[34:49], v229, v115, v[34:49]
	v_mfma_f32_32x32x2_f32 v[34:49], v232, v116, v[34:49]
	v_mfma_f32_32x32x2_f32 v[34:49], v233, v117, v[34:49]
	v_mfma_f32_32x32x2_f32 v[34:49], v234, v118, v[34:49]
	v_mfma_f32_32x32x2_f32 v[34:49], v235, v119, v[34:49]
	v_mfma_f32_32x32x2_f32 v[34:49], v245, v120, v[34:49]
	v_mfma_f32_32x32x2_f32 v[34:49], v246, v121, v[34:49]
	v_mfma_f32_32x32x2_f32 v[34:49], v247, v122, v[34:49]
	v_mfma_f32_32x32x2_f32 v[34:49], v248, v123, v[34:49]
	v_mfma_f32_32x32x2_f32 v[34:49], v249, v124, v[34:49]
	v_mfma_f32_32x32x2_f32 v[34:49], v250, v125, v[34:49]
	v_mfma_f32_32x32x2_f32 v[34:49], v251, v126, v[34:49]
	v_mfma_f32_32x32x2_f32 v[34:49], v143, v127, v[34:49]
	s_nop 15
	s_nop 3
	ds_write_b32 v130, v34 offset:128
	ds_write_b32 v130, v35 offset:388
	ds_write_b32 v130, v36 offset:648
	ds_write_b32 v130, v37 offset:908
	ds_write_b32 v130, v38 offset:2208
	ds_write_b32 v130, v39 offset:2468
	ds_write_b32 v130, v40 offset:2728
	ds_write_b32 v130, v41 offset:2988
	ds_write_b32 v130, v42 offset:4288
	ds_write_b32 v130, v43 offset:4548
	ds_write_b32 v130, v44 offset:4808
	ds_write_b32 v130, v45 offset:5068
	ds_write_b32 v130, v46 offset:6368
	ds_write_b32 v130, v47 offset:6628
	ds_write_b32 v130, v48 offset:6888
	ds_write_b32 v130, v49 offset:7148
.Lmy_fg_join:
	s_waitcnt lgkmcnt(0)
	s_barrier
	s_and_saveexec_b64 s[18:19], s[6:7]
	s_cbranch_execz .LBB0_891
	s_mov_b64 s[36:37], 0
	v_mov_b32_e32 v6, v18
	s_branch .LBB0_898
